# ml_state_pass: log-sigmoid via v_log/v_rcp (10 ops) instead of libm log1pf, wave scans via DPP row_shr/row_bcast instead of ds_bpermute, vmcnt ladder per wave; QKV GEMM second-round tiles rotated to i
# speedup vs baseline: 1.0246x; 1.0128x over previous
.LBB0_447:
	s_add_i32 s24, s58, 1
	s_cmp_lg_u32 s58, 33
	s_cselect_b64 s[40:41], -1, 0
	s_cmp_eq_u32 s58, 33
	s_cbranch_scc1 .LBB0_451
	s_cmp_lg_u32 s58, 0
	s_cselect_b32 s44, s54, 0
	s_and_b64 s[42:43], s[18:19], exec
	s_cselect_b32 s42, s24, s44
	s_lshl_b32 s43, s42, 7
	s_or_b32 s44, s43, s52
	s_add_i32 s43, s43, s53
	s_cmp_lt_u32 s42, 2
	s_cselect_b32 s42, s44, s43
	s_ashr_i32 s43, s42, 31
	s_lshl_b64 s[44:45], s[42:43], 1
	v_lshl_add_u64 v[8:9], v[30:31], 0, s[44:45]
	v_lshl_add_u64 v[0:1], v[8:9], 0, v[38:39]
	v_lshl_add_u64 v[4:5], v[8:9], 0, v[40:41]
	v_lshl_add_u64 v[10:11], v[8:9], 0, v[42:43]
	v_lshl_add_u64 v[12:13], v[8:9], 0, v[44:45]
	v_lshl_add_u64 v[16:17], v[50:51], 0, s[44:45]
	global_load_dwordx4 v[0:3], v[0:1], off
	s_nop 0
	global_load_dwordx4 v[4:7], v[4:5], off
	s_nop 0
	global_load_dwordx4 v[8:11], v[10:11], off
	s_nop 0
	global_load_dwordx4 v[12:15], v[12:13], off
	v_mov_b32_e32 v88, 0
	global_load_dwordx4 v[16:19], v[16:17], off
	s_and_saveexec_b64 s[44:45], s[2:3]
	s_cbranch_execz .LBB0_450
	v_or_b32_e32 v62, s42, v71
	s_movk_i32 s42, 0x140
	v_mad_i64_i32 v[62:63], s[42:43], v62, s42, v[52:53]
	global_load_dword v88, v[62:63], off offset:256

.LBB0_451:
	s_bitcmp1_b32 s58, 0
	s_cselect_b32 s42, 0xae00, 0
	s_add_i32 s44, s42, 0
	v_lshl_add_u32 v62, v46, 2, s44
	ds_read2st64_b32 v[64:65], v62 offset0:186 offset1:188
	v_lshl_add_u32 v62, v48, 2, s44
	ds_read2st64_b32 v[62:63], v62 offset0:186 offset1:188
	s_waitcnt lgkmcnt(0)
	s_waitcnt lgkmcnt(0)
	v_add_f32_e32 v111, v86, v64
	v_add_f32_e32 v112, v86, v62
	v_add_f32_e32 v114, v87, v65
	v_add_f32_e32 v115, v87, v63
	v_min_f32_e32 v116, 0, v114
	v_min_f32_e32 v117, 0, v115
	v_mul_f32_e64 v114, |v114|, s80
	v_mul_f32_e64 v115, |v115|, s80
	v_exp_f32_e32 v114, v114
	v_exp_f32_e32 v115, v115
	s_nop 0
	v_add_f32_e32 v118, 1.0, v114
	v_add_f32_e32 v119, 1.0, v115
	v_log_f32_e32 v62, v118
	v_log_f32_e32 v64, v119
	v_rcp_f32_e32 v63, v118
	v_rcp_f32_e32 v65, v119
	v_add_f32_e32 v118, -1.0, v118
	v_add_f32_e32 v119, -1.0, v119
	v_sub_f32_e32 v114, v114, v118
	v_sub_f32_e32 v115, v115, v119
	v_mul_f32_e32 v114, v114, v63
	v_mul_f32_e32 v115, v115, v65
	v_fmamk_f32 v62, v62, 0x3f317218, v114
	v_fmamk_f32 v64, v64, 0x3f317218, v115
	v_sub_f32_e32 v118, v116, v62
	v_sub_f32_e32 v62, v117, v64
	v_add_f32_e32 v63, v118, v62
	s_nop 1
	v_add_f32_dpp v63, v63, v63 row_shr:1 row_mask:0xf bank_mask:0xf
	s_nop 1
	v_add_f32_dpp v63, v63, v63 row_shr:2 row_mask:0xf bank_mask:0xf
	s_nop 1
	v_add_f32_dpp v63, v63, v63 row_shr:4 row_mask:0xf bank_mask:0xf
	s_nop 1
	v_add_f32_dpp v63, v63, v63 row_shr:8 row_mask:0xf bank_mask:0xf
	s_nop 1
	v_add_f32_dpp v63, v63, v63 row_bcast:15 row_mask:0xa bank_mask:0xf
	s_nop 1
	v_add_f32_dpp v63, v63, v63 row_bcast:31 row_mask:0xc bank_mask:0xf
	v_mov_b32_e32 v109, v63
	v_sub_f32_e32 v110, v109, v62
	v_sub_f32_e32 v62, v111, v110
	v_sub_f32_e32 v64, v112, v109
	v_max_f32_e32 v111, v62, v64
	s_nop 1
	v_max_f32_dpp v111, v111, v111 row_shr:1 row_mask:0xf bank_mask:0xf
	s_nop 1
	v_max_f32_dpp v111, v111, v111 row_shr:2 row_mask:0xf bank_mask:0xf
	s_nop 1
	v_max_f32_dpp v111, v111, v111 row_shr:4 row_mask:0xf bank_mask:0xf
	s_nop 1
	v_max_f32_dpp v111, v111, v111 row_shr:8 row_mask:0xf bank_mask:0xf
	s_nop 1
	v_max_f32_dpp v111, v111, v111 row_bcast:15 row_mask:0xa bank_mask:0xf
	s_nop 1
	v_max_f32_dpp v111, v111, v111 row_bcast:31 row_mask:0xc bank_mask:0xf
	ds_bpermute_b32 v112, v89, v111
	v_readlane_b32 s42, v111, 63
	v_readlane_b32 s43, v109, 63
	v_max_f32_e32 v113, v61, v61
	s_nop 1
	v_max_f32_e32 v65, s42, v113
	v_mov_b32_e32 v63, s43
	v_sub_f32_e32 v113, v62, v65
	v_mul_f32_e32 v113, 0x3fb8aa3b, v113
	v_exp_f32_e32 v113, v113
	ds_write_b32 v96, v113
	v_sub_f32_e32 v113, v64, v65
	v_mul_f32_e32 v113, 0x3fb8aa3b, v113
	v_exp_f32_e32 v113, v113
	ds_write_b32 v97, v113
	s_and_saveexec_b64 s[42:43], s[34:35]
	s_cbranch_execz .LBB0_454
	s_cmp_gt_u32 s58, 1
	s_cselect_b32 s45, 35, 1
	s_add_i32 s45, s45, s54
	s_sub_i32 s45, s45, 34
	s_and_b64 s[60:61], s[18:19], exec
	s_cselect_b32 s45, s58, s45
	s_lshl_b32 s59, s45, 7
	s_cmp_lt_i32 s45, 2
	s_cselect_b32 s45, s52, s53
	s_add_i32 s60, s45, s59
	s_ashr_i32 s61, s60, 31
	s_lshl_b64 s[60:61], s[60:61], 2
	s_add_u32 s60, s56, s60
	s_addc_u32 s61, s57, s61
	v_mov_b32_e32 v113, 0xf149f2ca
	s_add_u32 s62, s60, 0x88000
	s_waitcnt lgkmcnt(2)
	v_cndmask_b32_e64 v112, v112, v113, s[4:5]
	s_addc_u32 s63, s61, 0
	v_max_f32_e32 v112, v112, v112
	v_max_f32_e32 v113, v62, v62
	global_store_dword v100, v110, s[60:61]
	global_store_dword v101, v109, s[60:61]
	s_add_u32 s60, s60, 0x110000
	v_max_f32_e32 v112, v112, v113
	s_addc_u32 s61, s61, 0
	global_store_dword v100, v62, s[62:63]
	global_store_dword v101, v64, s[62:63]
	global_store_dword v100, v112, s[60:61]
	global_store_dword v101, v111, s[60:61]
	s_and_b64 exec, exec, s[4:5]
	s_cbranch_execz .LBB0_454
	s_add_i32 s58, s55, s58
	s_ashr_i32 s59, s58, 31
	s_lshl_b64 s[58:59], s[58:59], 2
	s_add_u32 s58, s49, s58
	s_addc_u32 s59, s50, s59
	global_store_dword v161, v61, s[58:59]

.LBB0_456:
	s_or_b64 exec, exec, s[42:43]
	v_sub_f32_e32 v61, v61, v65
	v_mul_f32_e32 v61, 0x3fb8aa3b, v61
	v_exp_f32_e32 v64, v61
	v_cvt_pk_bf16_f32 v61, v20, v161
	global_store_short v[56:57], v61, off offset:-512
	v_cvt_pk_bf16_f32 v61, v105, v161
	global_store_short v[56:57], v61, off offset:-256
	v_cvt_pk_bf16_f32 v61, v106, v161
	global_store_short v[56:57], v61, off
	v_cvt_pk_bf16_f32 v61, v107, v161
	v_or_b32_e32 v106, 0x1000, v54
	v_mov_b32_e32 v107, v55
	global_store_short v[56:57], v61, off offset:256
	v_cvt_pk_bf16_f32 v61, v108, v161
	v_lshl_add_u64 v[106:107], v[32:33], 0, v[106:107]
	global_store_short v[106:107], v61, off
	v_cvt_pk_bf16_f32 v61, v104, v161
	v_or_b32_e32 v104, 0x1100, v54
	v_mov_b32_e32 v105, v55
	v_lshl_add_u64 v[104:105], v[32:33], 0, v[104:105]
	global_store_short v[104:105], v61, off
	v_or_b32_e32 v104, 0x1200, v54
	v_mov_b32_e32 v105, v55
	v_cvt_pk_bf16_f32 v61, v103, v161
	v_lshl_add_u64 v[104:105], v[32:33], 0, v[104:105]
	global_store_short v[104:105], v61, off
	v_cvt_pk_bf16_f32 v61, v102, v161
	v_or_b32_e32 v102, 0x1300, v54
	v_mov_b32_e32 v103, v55
	v_lshl_add_u64 v[102:103], v[32:33], 0, v[102:103]
	global_store_short v[102:103], v61, off
	s_waitcnt lgkmcnt(0)
	v_lshl_add_u32 v61, v75, 1, s44
	v_add_u32_e32 v62, v61, v77
	ds_read_b128 v[102:105], v76
	ds_read_b128 v[106:109], v76 offset:16
	s_waitcnt lgkmcnt(5)
	ds_read_b128 v[110:113], v62 offset:4096
	v_add_u32_e32 v61, v61, v84
	v_pk_mul_f32 v[22:23], v[22:23], v[64:65] op_sel_hi:[1,0]
	v_pk_mul_f32 v[20:21], v[20:21], v[64:65] op_sel_hi:[1,0]
	v_pk_mul_f32 v[26:27], v[26:27], v[64:65] op_sel_hi:[1,0]
	s_waitcnt lgkmcnt(0)
	v_lshlrev_b32_e32 v114, 16, v110
	v_and_b32_e32 v110, 0xffff0000, v110
	v_lshlrev_b32_e32 v115, 16, v111
	v_and_b32_e32 v111, 0xffff0000, v111
	v_lshlrev_b32_e32 v116, 16, v112
	v_and_b32_e32 v112, 0xffff0000, v112
	v_lshlrev_b32_e32 v117, 16, v113
	v_and_b32_e32 v113, 0xffff0000, v113
	v_mul_f32_e32 v102, v102, v114
	v_mul_f32_e32 v103, v103, v110
	v_mul_f32_e32 v104, v104, v115
	v_mul_f32_e32 v114, v106, v116
	v_fma_f32 v116, v106, v116, v102
	v_mul_f32_e32 v106, v107, v112
	v_fma_f32 v110, v107, v112, v103
	v_mul_f32_e32 v107, v108, v117
	v_fma_f32 v112, v108, v117, v104
	v_mul_f32_e32 v105, v105, v111
	v_mul_f32_e32 v108, v109, v113
	v_fma_f32 v111, v109, v113, v105
	v_cvt_pk_bf16_f32 v102, v102, v103
	v_cvt_pk_bf16_f32 v103, v104, v105
	v_cvt_pk_bf16_f32 v104, v114, v106
	v_cvt_pk_bf16_f32 v105, v107, v108
	ds_read_b128 v[106:109], v61 offset:38912
	s_waitcnt lgkmcnt(0)
	v_mfma_f32_16x16x32_bf16 v[20:23], v[106:109], v[102:105], v[20:23]
	ds_read_b128 v[106:109], v61 offset:43264
	v_pk_mul_f32 v[24:25], v[24:25], v[64:65] op_sel_hi:[1,0]
	s_waitcnt lgkmcnt(0)
	s_nop 0
	v_mfma_f32_16x16x32_bf16 v[24:27], v[106:109], v[102:105], v[24:27]
	v_add_f32_e32 v102, 0, v116
	v_add_f32_e32 v102, v110, v102
	v_add_f32_e32 v102, v112, v102
	v_add_f32_e32 v114, v111, v102
	ds_read_b128 v[102:105], v76 offset:128
	ds_read_b128 v[106:109], v76 offset:144
	ds_read_b128 v[110:113], v62 offset:4160
	s_waitcnt lgkmcnt(0)
	v_lshlrev_b32_e32 v115, 16, v110
	v_and_b32_e32 v110, 0xffff0000, v110
	v_lshlrev_b32_e32 v116, 16, v111
	v_and_b32_e32 v111, 0xffff0000, v111
	v_lshlrev_b32_e32 v117, 16, v112
	v_and_b32_e32 v112, 0xffff0000, v112
	v_lshlrev_b32_e32 v118, 16, v113
	v_and_b32_e32 v113, 0xffff0000, v113
	v_mul_f32_e32 v102, v102, v115
	v_mul_f32_e32 v103, v103, v110
	v_mul_f32_e32 v104, v104, v116
	v_mul_f32_e32 v115, v106, v117
	v_fma_f32 v117, v106, v117, v102
	v_mul_f32_e32 v106, v107, v112
	v_fma_f32 v110, v107, v112, v103
	v_mul_f32_e32 v107, v108, v118
	v_fma_f32 v112, v108, v118, v104
	v_mul_f32_e32 v105, v105, v111
	v_mul_f32_e32 v108, v109, v113
	v_fma_f32 v111, v109, v113, v105
	v_cvt_pk_bf16_f32 v102, v102, v103
	v_cvt_pk_bf16_f32 v103, v104, v105
	v_cvt_pk_bf16_f32 v104, v115, v106
	v_cvt_pk_bf16_f32 v105, v107, v108
	ds_read_b128 v[106:109], v61 offset:38976
	s_waitcnt lgkmcnt(0)
	v_mfma_f32_16x16x32_bf16 v[20:23], v[106:109], v[102:105], v[20:23]
	ds_read_b128 v[106:109], v61 offset:43328
	s_waitcnt lgkmcnt(0)
	v_mfma_f32_16x16x32_bf16 v[24:27], v[106:109], v[102:105], v[24:27]
	v_add_f32_e32 v102, v114, v117
	v_add_f32_e32 v102, v110, v102
	v_add_f32_e32 v102, v112, v102
	v_add_f32_e32 v114, v111, v102
	ds_read_b128 v[102:105], v76 offset:256
	ds_read_b128 v[106:109], v76 offset:272
	ds_read_b128 v[110:113], v62 offset:4224
	s_waitcnt lgkmcnt(0)
	v_lshlrev_b32_e32 v115, 16, v110
	v_and_b32_e32 v110, 0xffff0000, v110
	v_lshlrev_b32_e32 v116, 16, v111
	v_and_b32_e32 v111, 0xffff0000, v111
	v_lshlrev_b32_e32 v117, 16, v112
	v_and_b32_e32 v112, 0xffff0000, v112
	v_lshlrev_b32_e32 v118, 16, v113
	v_and_b32_e32 v113, 0xffff0000, v113
	v_mul_f32_e32 v102, v102, v115
	v_mul_f32_e32 v103, v103, v110
	v_mul_f32_e32 v104, v104, v116
	v_mul_f32_e32 v115, v106, v117
	v_fma_f32 v117, v106, v117, v102
	v_mul_f32_e32 v106, v107, v112
	v_fma_f32 v110, v107, v112, v103
	v_mul_f32_e32 v107, v108, v118
	v_fma_f32 v112, v108, v118, v104
	v_mul_f32_e32 v105, v105, v111
	v_mul_f32_e32 v108, v109, v113
	v_fma_f32 v111, v109, v113, v105
	v_cvt_pk_bf16_f32 v102, v102, v103
	v_cvt_pk_bf16_f32 v103, v104, v105
	v_cvt_pk_bf16_f32 v104, v115, v106
	v_cvt_pk_bf16_f32 v105, v107, v108
	ds_read_b128 v[106:109], v61 offset:39040
	s_waitcnt lgkmcnt(0)
	v_mfma_f32_16x16x32_bf16 v[20:23], v[106:109], v[102:105], v[20:23]
	ds_read_b128 v[106:109], v61 offset:43392
	s_waitcnt lgkmcnt(0)
	v_mfma_f32_16x16x32_bf16 v[24:27], v[106:109], v[102:105], v[24:27]
	v_add_f32_e32 v102, v114, v117
	v_add_f32_e32 v102, v110, v102
	v_add_f32_e32 v102, v112, v102
	v_add_f32_e32 v114, v111, v102
	ds_read_b128 v[102:105], v76 offset:384
	ds_read_b128 v[106:109], v76 offset:400
	ds_read_b128 v[110:113], v62 offset:4288
	s_waitcnt lgkmcnt(0)
	v_lshlrev_b32_e32 v62, 16, v110
	v_and_b32_e32 v110, 0xffff0000, v110
	v_lshlrev_b32_e32 v115, 16, v111
	v_and_b32_e32 v111, 0xffff0000, v111
	v_lshlrev_b32_e32 v116, 16, v112
	v_and_b32_e32 v112, 0xffff0000, v112
	v_lshlrev_b32_e32 v117, 16, v113
	v_and_b32_e32 v113, 0xffff0000, v113
	v_mul_f32_e32 v62, v102, v62
	v_mul_f32_e32 v102, v103, v110
	v_mul_f32_e32 v118, v106, v116
	v_fma_f32 v116, v106, v116, v62
	v_mul_f32_e32 v106, v107, v112
	v_fma_f32 v110, v107, v112, v102
	v_mul_f32_e32 v103, v104, v115
	v_mul_f32_e32 v107, v108, v117
	v_mul_f32_e32 v104, v105, v111
	v_mul_f32_e32 v105, v109, v113
	v_fma_f32 v112, v108, v117, v103
	v_fma_f32 v111, v109, v113, v104
	v_cvt_pk_bf16_f32 v102, v62, v102
	v_cvt_pk_bf16_f32 v103, v103, v104
	v_cvt_pk_bf16_f32 v104, v118, v106
	v_cvt_pk_bf16_f32 v105, v107, v105
	ds_read_b128 v[106:109], v61 offset:39104
	s_waitcnt lgkmcnt(0)
	v_mfma_f32_16x16x32_bf16 v[20:23], v[106:109], v[102:105], v[20:23]
	ds_read_b128 v[106:109], v61 offset:43456
	v_add_f32_e32 v61, v114, v116
	v_add_f32_e32 v61, v110, v61
	v_add_f32_e32 v61, v112, v61
	v_add_f32_e32 v61, v111, v61
	ds_bpermute_b32 v62, v98, v61
	s_waitcnt lgkmcnt(1)
	v_mfma_f32_16x16x32_bf16 v[24:27], v[106:109], v[102:105], v[24:27]
	s_waitcnt lgkmcnt(0)
	v_add_f32_e32 v61, v61, v62
	ds_bpermute_b32 v62, v99, v61
	s_andn2_b64 vcc, exec, s[40:41]
	s_cbranch_vccnz .LBB0_446
	s_bitcmp1_b32 s24, 0
	s_cselect_b32 s40, 0xae00, 0
	s_add_i32 s42, s40, 0
	v_add_u32_e32 v102, s42, v73
	v_add_u32_e32 v103, s42, v81
	s_cmp_lg_u64 s[34:35], 0
	s_cbranch_scc1 .Lmls_lad16
	s_cmp_lg_u64 s[36:37], 0
	s_cbranch_scc1 .Lmls_lad9
	s_waitcnt vmcnt(12)
	ds_write_b128 v102, v[0:3] offset:4096
	s_waitcnt vmcnt(11)
	ds_write_b128 v103, v[4:7] offset:4096
	v_add_u32_e32 v103, s42, v82
	s_waitcnt vmcnt(10)
	ds_write_b128 v103, v[8:11] offset:4096
	v_add_u32_e32 v103, s42, v83
	s_waitcnt vmcnt(9)
	ds_write_b128 v103, v[12:15] offset:4096
	s_waitcnt vmcnt(8)
	s_branch .Lmls_lad_done
.Lmls_lad9:
	s_waitcnt vmcnt(13)
	ds_write_b128 v102, v[0:3] offset:4096
	s_waitcnt vmcnt(12)
	ds_write_b128 v103, v[4:7] offset:4096
	v_add_u32_e32 v103, s42, v82
	s_waitcnt vmcnt(11)
	ds_write_b128 v103, v[8:11] offset:4096
	v_add_u32_e32 v103, s42, v83
	s_waitcnt vmcnt(10)
	ds_write_b128 v103, v[12:15] offset:4096
	s_waitcnt vmcnt(9)
	s_branch .Lmls_lad_done
.Lmls_lad16:
	s_waitcnt vmcnt(20)
	ds_write_b128 v102, v[0:3] offset:4096
	s_waitcnt vmcnt(19)
	ds_write_b128 v103, v[4:7] offset:4096
	v_add_u32_e32 v103, s42, v82
	s_waitcnt vmcnt(18)
	ds_write_b128 v103, v[8:11] offset:4096
	v_add_u32_e32 v103, s42, v83
	s_waitcnt vmcnt(17)
	ds_write_b128 v103, v[12:15] offset:4096
	s_waitcnt vmcnt(16)
.Lmls_lad_done:
	ds_write_b128 v102, v[16:19] offset:38912
	s_and_saveexec_b64 s[40:41], s[2:3]
	s_cbranch_execz .LBB0_445
	v_lshl_add_u32 v102, v29, 2, s42
	ds_write_b32 v102, v88 offset:47616
	s_branch .LBB0_445

.LBB0_523:
	s_add_i32 s46, s46, 1
	v_readlane_b32 s2, v252, 63
	s_mul_i32 s2, s46, s2
	s_mul_hi_u32 s3, s46, s33
	s_add_i32 s3, s3, s2
	s_mul_i32 s2, s46, s33
	v_readlane_b32 s11, v253, 14
	s_add_u32 s14, s2, s11
	v_readlane_b32 s2, v252, 62
	s_addc_u32 s15, s3, s2
	s_cmp_eq_u32 s33, 0x100
	s_cbranch_scc0 .Lrot_q_done
	s_cmp_lt_u32 s11, 104
	s_cselect_b32 s2, 0x100000, 0
	s_add_u32 s14, s14, s2
	s_addc_u32 s15, s15, 0
	s_sub_u32 s14, s14, 104
	s_subb_u32 s15, s15, 0
.Lrot_q_done:
	v_cmp_gt_i64_e32 vcc, s[14:15], v[166:167]
	v_cmp_lt_i64_e64 s[2:3], s[14:15], v[164:165]
	s_cbranch_vccnz .LBB0_525
	s_ashr_i32 s10, s14, 31
	s_lshr_b32 s10, s10, 29
	s_add_i32 s10, s14, s10
	s_ashr_i32 s11, s10, 3
	s_and_b32 s10, s10, -8
	s_sub_i32 s10, s14, s10
	s_cmp_lt_i32 s10, 0
	s_cselect_b32 s12, 52, 51
	s_mul_i32 s10, s10, s12
	s_add_i32 s10, s10, s11
	s_mul_hi_i32 s11, s10, 0x2aaaaaab
	s_lshr_b32 s12, s11, 31
	s_ashr_i32 s11, s11, 3
	s_add_i32 s11, s11, s12
	s_lshl_b32 s12, s11, 3
	s_sub_i32 s13, 0x44, s12
	s_min_i32 s13, s13, 8
	s_abs_i32 s14, s13
	v_cvt_f32_u32_e32 v0, s14
	s_sub_i32 s16, 0, s14
	s_mul_i32 s11, s11, 48
	s_sub_i32 s11, s10, s11
	v_rcp_iflag_f32_e32 v0, v0
	s_abs_i32 s10, s11
	s_xor_b32 s15, s11, s13
	s_ashr_i32 s15, s15, 31
	v_mul_f32_e32 v0, 0x4f7ffffe, v0
	v_cvt_u32_f32_e32 v0, v0
	s_nop 0
	v_readfirstlane_b32 s17, v0
	s_mul_i32 s16, s16, s17
	s_mul_hi_u32 s16, s17, s16
	s_add_i32 s17, s17, s16
	s_mul_hi_u32 s16, s10, s17
	s_mul_i32 s17, s16, s14
	s_sub_i32 s10, s10, s17
	s_add_i32 s30, s16, 1
	s_sub_i32 s17, s10, s14
	s_cmp_ge_u32 s10, s14
	s_cselect_b32 s16, s30, s16
	s_cselect_b32 s10, s17, s10
	s_add_i32 s17, s16, 1
	s_cmp_ge_u32 s10, s14
	s_cselect_b32 s10, s17, s16
	s_xor_b32 s10, s10, s15
	s_sub_i32 s10, s10, s15
	s_mul_i32 s13, s10, s13
	s_sub_i32 s11, s11, s13
	s_add_i32 s12, s12, s11

.LBB0_539:
	s_add_i32 s46, s46, 1
	v_readlane_b32 s4, v252, 63
	s_mul_i32 s4, s46, s4
	s_mul_hi_u32 s5, s46, s33
	s_add_i32 s5, s5, s4
	s_mul_i32 s4, s46, s33
	v_readlane_b32 s13, v253, 14
	s_add_u32 s16, s4, s13
	v_readlane_b32 s4, v252, 62
	s_addc_u32 s17, s5, s4
	s_cmp_eq_u32 s33, 0x100
	s_cbranch_scc0 .Lrot_k_done
	s_cmp_lt_u32 s13, 88
	s_cselect_b32 s4, 0x100000, 0
	s_add_u32 s16, s16, s4
	s_addc_u32 s17, s17, 0
	s_sub_u32 s16, s16, 88
	s_subb_u32 s17, s17, 0
.Lrot_k_done:
	v_cmp_gt_i64_e32 vcc, s[16:17], v[170:171]
	v_cmp_lt_i64_e64 s[4:5], s[16:17], v[168:169]
	s_cbranch_vccnz .LBB0_541
	s_ashr_i32 s12, s16, 31
	s_lshr_b32 s12, s12, 29
	s_add_i32 s12, s16, s12
	s_ashr_i32 s13, s12, 3
	s_and_b32 s12, s12, -8
	s_sub_i32 s12, s16, s12
	s_cmp_lt_i32 s12, 0
	s_cselect_b32 s14, 35, 34
	s_mul_i32 s12, s12, s14
	s_add_i32 s12, s12, s13
	s_ashr_i32 s13, s12, 31
	s_lshr_b32 s13, s13, 27
	s_add_i32 s13, s12, s13
	s_ashr_i32 s14, s13, 5
	s_lshl_b32 s14, s14, 3
	s_sub_i32 s15, 0x44, s14
	s_min_i32 s15, s15, 8
	s_abs_i32 s16, s15
	v_cvt_f32_u32_e32 v0, s16
	s_sub_i32 s18, 0, s16
	s_andn2_b32 s13, s13, 31
	s_sub_i32 s13, s12, s13
	v_rcp_iflag_f32_e32 v0, v0
	s_abs_i32 s12, s13
	s_xor_b32 s17, s13, s15
	s_ashr_i32 s17, s17, 31
	v_mul_f32_e32 v0, 0x4f7ffffe, v0
	v_cvt_u32_f32_e32 v0, v0
	s_nop 0
	v_readfirstlane_b32 s19, v0
	s_mul_i32 s18, s18, s19
	s_mul_hi_u32 s18, s19, s18
	s_add_i32 s19, s19, s18
	s_mul_hi_u32 s18, s12, s19
	s_mul_i32 s19, s18, s16
	s_sub_i32 s12, s12, s19
	s_add_i32 s30, s18, 1
	s_sub_i32 s19, s12, s16
	s_cmp_ge_u32 s12, s16
	s_cselect_b32 s18, s30, s18
	s_cselect_b32 s12, s19, s12
	s_add_i32 s19, s18, 1
	s_cmp_ge_u32 s12, s16
	s_cselect_b32 s12, s19, s18
	s_xor_b32 s12, s12, s17
	s_sub_i32 s12, s12, s17
	s_mul_i32 s15, s12, s15
	s_sub_i32 s13, s13, s15
	s_add_i32 s14, s14, s13

.LBB0_555:
	s_add_i32 s44, s44, 1
	v_readlane_b32 s2, v252, 63
	s_mul_i32 s2, s44, s2
	s_mul_hi_u32 s3, s44, s33
	s_add_i32 s3, s3, s2
	s_mul_i32 s2, s44, s33
	v_readlane_b32 s11, v253, 14
	s_add_u32 s14, s2, s11
	v_readlane_b32 s2, v252, 62
	s_addc_u32 s15, s3, s2
	s_cmp_eq_u32 s33, 0x100
	s_cbranch_scc0 .Lrot_v_done
	s_cmp_lt_u32 s11, 72
	s_cselect_b32 s2, 0x100000, 0
	s_add_u32 s14, s14, s2
	s_addc_u32 s15, s15, 0
	s_sub_u32 s14, s14, 72
	s_subb_u32 s15, s15, 0
.Lrot_v_done:
	v_cmp_gt_i64_e32 vcc, s[14:15], v[170:171]
	v_cmp_lt_i64_e64 s[2:3], s[14:15], v[168:169]
	s_cbranch_vccnz .LBB0_557
	s_ashr_i32 s10, s14, 31
	s_lshr_b32 s10, s10, 29
	s_add_i32 s10, s14, s10
	s_ashr_i32 s11, s10, 3
	s_and_b32 s10, s10, -8
	s_sub_i32 s10, s14, s10
	s_cmp_lt_i32 s10, 0
	s_cselect_b32 s12, 35, 34
	s_mul_i32 s10, s10, s12
	s_add_i32 s10, s10, s11
	s_mul_hi_i32 s11, s10, 0x78787879
	s_lshr_b32 s12, s11, 31
	s_ashr_i32 s11, s11, 8
	s_add_i32 s11, s11, s12
	s_lshl_b32 s12, s11, 3
	s_sub_i32 s13, 4, s12
	s_min_i32 s13, s13, 8
	s_abs_i32 s14, s13
	v_cvt_f32_u32_e32 v0, s14
	s_sub_i32 s16, 0, s14
	s_mulk_i32 s11, 0x220
	s_sub_i32 s11, s10, s11
	v_rcp_iflag_f32_e32 v0, v0
	s_abs_i32 s10, s11
	s_xor_b32 s15, s11, s13
	s_ashr_i32 s15, s15, 31
	v_mul_f32_e32 v0, 0x4f7ffffe, v0
	v_cvt_u32_f32_e32 v0, v0
	s_nop 0
	v_readfirstlane_b32 s17, v0
	s_mul_i32 s16, s16, s17
	s_mul_hi_u32 s16, s17, s16
	s_add_i32 s17, s17, s16
	s_mul_hi_u32 s16, s10, s17
	s_mul_i32 s17, s16, s14
	s_sub_i32 s10, s10, s17
	s_add_i32 s28, s16, 1
	s_sub_i32 s17, s10, s14
	s_cmp_ge_u32 s10, s14
	s_cselect_b32 s16, s28, s16
	s_cselect_b32 s10, s17, s10
	s_add_i32 s17, s16, 1
	s_cmp_ge_u32 s10, s14
	s_cselect_b32 s10, s17, s16
	s_xor_b32 s10, s10, s15
	s_sub_i32 s10, s10, s15
	s_mul_i32 s13, s10, s13
	s_sub_i32 s11, s11, s13
	s_add_i32 s12, s12, s11
